# add: grid-barrier leader L1 invalidate also issued before its cross-XCD spin
# speedup vs baseline: 1.0052x; 1.0018x over previous
.LBB0_82:
	s_andn2_saveexec_b64 s[4:5], s[4:5]
	s_cbranch_execz .LBB0_102
	s_mov_b64 s[6:7], exec
	buffer_wbl2 sc1
	s_waitcnt lgkmcnt(0)
	s_waitcnt vmcnt(0)
	buffer_inv sc1
	v_mbcnt_lo_u32_b32 v1, s6, 0
	v_mbcnt_hi_u32_b32 v1, s7, v1
	v_cmp_eq_u32_e32 vcc, 0, v1
	s_and_saveexec_b64 s[8:9], vcc
	s_cbranch_execz .LBB0_85
	s_load_dwordx4 s[16:19], s[0:1], 0xa0
	s_bcnt1_i32_b64 s6, s[6:7]
	v_mov_b32_e32 v2, 0x7000
	v_mov_b32_e32 v3, s6
	s_waitcnt lgkmcnt(0)
	global_atomic_add v2, v2, v3, s[18:19] offset:1024 sc0

.LBB0_99:
	s_or_b64 exec, exec, s[6:7]
	s_mov_b64 s[6:7], exec
	v_mbcnt_lo_u32_b32 v0, s6, 0
	v_mbcnt_hi_u32_b32 v0, s7, v0
	s_mov_b32 s11, 0
	v_cmp_eq_u32_e32 vcc, 0, v0
	s_waitcnt vmcnt(0)
	s_and_saveexec_b64 s[8:9], vcc
	s_cbranch_execz .LBB0_101
	s_add_i32 s10, s14, 0x900
	s_lshl_b64 s[10:11], s[10:11], 2
	v_readlane_b32 s12, v252, 44
	v_readlane_b32 s13, v252, 45
	s_add_u32 s10, s12, s10
	s_addc_u32 s11, s13, s11
	s_bcnt1_i32_b64 s6, s[6:7]
	v_mov_b32_e32 v0, 0
	v_mov_b32_e32 v1, s6
	global_atomic_add v0, v1, s[10:11]

.LBB0_420:
	s_andn2_saveexec_b64 s[2:3], s[2:3]
	s_cbranch_execz .LBB0_440
	s_mov_b64 s[2:3], exec
	buffer_wbl2 sc1
	s_waitcnt lgkmcnt(0)
	s_waitcnt vmcnt(0)
	buffer_inv sc1
	v_mbcnt_lo_u32_b32 v0, s2, 0
	v_mbcnt_hi_u32_b32 v0, s3, v0
	v_cmp_eq_u32_e32 vcc, 0, v0
	s_and_saveexec_b64 s[4:5], vcc
	s_cbranch_execz .LBB0_423
	s_bcnt1_i32_b64 s2, s[2:3]
	v_mov_b32_e32 v3, s2
	v_readlane_b32 s2, v253, 30
	v_readlane_b32 s3, v253, 31
	s_nop 4
	global_atomic_add v3, v1, v3, s[2:3] sc0

.LBB0_437:
	s_or_b64 exec, exec, s[2:3]
	s_mov_b64 s[2:3], exec
	v_mbcnt_lo_u32_b32 v0, s2, 0
	v_mbcnt_hi_u32_b32 v0, s3, v0
	v_cmp_eq_u32_e32 vcc, 0, v0
	s_waitcnt vmcnt(0)
	s_and_saveexec_b64 s[4:5], vcc
	s_cbranch_execz .LBB0_439
	s_add_i32 s86, s20, 0x900
	s_lshl_b64 s[6:7], s[86:87], 2
	v_readlane_b32 s8, v252, 44
	v_readlane_b32 s9, v252, 45
	s_add_u32 s6, s8, s6
	s_addc_u32 s7, s9, s7
	s_bcnt1_i32_b64 s2, s[2:3]
	v_mov_b32_e32 v0, s2
	global_atomic_add v1, v0, s[6:7]

.LBB0_1283:
	s_mov_b64 s[4:5], exec
	buffer_wbl2 sc1
	s_waitcnt lgkmcnt(0)
	s_waitcnt vmcnt(0)
	buffer_inv sc1
	v_mbcnt_lo_u32_b32 v0, s4, 0
	v_mbcnt_hi_u32_b32 v0, s5, v0
	v_cmp_eq_u32_e32 vcc, 0, v0
	s_and_saveexec_b64 s[6:7], vcc
	s_cbranch_execz .LBB0_1285
	s_bcnt1_i32_b64 s4, s[4:5]
	v_mov_b32_e32 v3, s4
	v_readlane_b32 s4, v253, 30
	v_readlane_b32 s5, v253, 31
	s_nop 4
	global_atomic_add v3, v1, v3, s[4:5] sc0

.LBB0_1299:
	s_or_b64 exec, exec, s[4:5]
	s_mov_b64 s[4:5], exec
	v_mbcnt_lo_u32_b32 v0, s4, 0
	v_mbcnt_hi_u32_b32 v0, s5, v0
	v_cmp_eq_u32_e32 vcc, 0, v0
	s_waitcnt vmcnt(0)
	s_and_saveexec_b64 s[6:7], vcc
	s_cbranch_execnz .LBB0_1300
	s_getpc_b64 s[98:99]
